# post phase of layer 0: input x rows loaded with the nt hint as well
# speedup vs baseline: 1.0113x; 1.0007x over previous
.LBB0_33:
	v_add_u32_e32 v50, -3, v122
	v_ashrrev_i32_e32 v51, 31, v50
	v_lshlrev_b64 v[162:163], 12, v[50:51]
	v_lshl_add_u64 v[52:53], v[114:115], 0, v[162:163]
	v_lshlrev_b64 v[160:161], 11, v[50:51]
	v_lshl_add_u64 v[50:51], v[116:117], 0, v[160:161]
	global_load_dwordx4 v[110:113], v[52:53], off nt
	global_load_dwordx2 v[170:171], v[50:51], off
	global_load_dwordx4 v[106:109], v[52:53], off offset:1024 nt
	global_load_dwordx2 v[168:169], v[50:51], off offset:512
	global_load_dwordx4 v[102:105], v[52:53], off offset:2048 nt
	global_load_dwordx2 v[166:167], v[50:51], off offset:1024
	global_load_dwordx4 v[98:101], v[52:53], off offset:3072 nt
	global_load_dwordx2 v[164:165], v[50:51], off offset:1536
	v_ashrrev_i32_e32 v123, 31, v122
	v_lshlrev_b64 v[126:127], 12, v[122:123]
	v_lshlrev_b64 v[124:125], 11, v[122:123]
	v_add_u32_e32 v50, -2, v122
	v_ashrrev_i32_e32 v51, 31, v50
	v_lshlrev_b64 v[150:151], 12, v[50:51]
	v_lshl_add_u64 v[52:53], v[114:115], 0, v[150:151]
	v_lshlrev_b64 v[140:141], 11, v[50:51]
	v_lshl_add_u64 v[50:51], v[116:117], 0, v[140:141]
	global_load_dwordx4 v[94:97], v[52:53], off nt
	global_load_dwordx2 v[158:159], v[50:51], off
	global_load_dwordx4 v[90:93], v[52:53], off offset:1024 nt
	global_load_dwordx2 v[156:157], v[50:51], off offset:512
	global_load_dwordx4 v[86:89], v[52:53], off offset:2048 nt
	global_load_dwordx2 v[154:155], v[50:51], off offset:1024
	global_load_dwordx4 v[82:85], v[52:53], off offset:3072 nt
	global_load_dwordx2 v[152:153], v[50:51], off offset:1536
	v_add_u32_e32 v50, -1, v122
	v_ashrrev_i32_e32 v51, 31, v50
	v_lshlrev_b64 v[138:139], 12, v[50:51]
	v_lshlrev_b64 v[136:137], 11, v[50:51]
	v_lshl_add_u64 v[52:53], v[114:115], 0, v[138:139]
	v_lshl_add_u64 v[50:51], v[116:117], 0, v[136:137]
	global_load_dwordx4 v[78:81], v[52:53], off nt
	global_load_dwordx2 v[148:149], v[50:51], off
	global_load_dwordx4 v[74:77], v[52:53], off offset:1024 nt
	global_load_dwordx2 v[146:147], v[50:51], off offset:512
	global_load_dwordx4 v[70:73], v[52:53], off offset:2048 nt
	global_load_dwordx2 v[144:145], v[50:51], off offset:1024
	global_load_dwordx4 v[66:69], v[52:53], off offset:3072 nt
	global_load_dwordx2 v[142:143], v[50:51], off offset:1536
	v_lshl_add_u64 v[50:51], v[114:115], 0, v[126:127]
	v_lshl_add_u64 v[128:129], v[116:117], 0, v[124:125]
	v_lshl_add_u64 v[162:163], v[120:121], 0, v[162:163]
	global_load_dwordx4 v[62:65], v[50:51], off nt
	global_load_dwordx2 v[134:135], v[128:129], off
	global_load_dwordx4 v[58:61], v[50:51], off offset:1024 nt
	global_load_dwordx2 v[132:133], v[128:129], off offset:512
	global_load_dwordx4 v[54:57], v[50:51], off offset:2048 nt
	global_load_dwordx2 v[130:131], v[128:129], off offset:1024
	s_nop 0
	global_load_dwordx4 v[50:53], v[50:51], off offset:3072 nt
	s_nop 0
	global_load_dwordx2 v[128:129], v[128:129], off offset:1536
	v_lshl_add_u64 v[160:161], v[118:119], 0, v[160:161]
	v_add_u32_e32 v172, s3, v172
	v_add_u32_e32 v122, s3, v122
	s_waitcnt vmcnt(30)
	v_and_b32_e32 v177, 0xffff0000, v170
	v_and_b32_e32 v179, 0xffff0000, v171
	v_lshlrev_b32_e32 v176, 16, v170
	v_lshlrev_b32_e32 v178, 16, v171
	v_mul_f32_e32 v0, v177, v177
	v_mul_f32_e32 v123, v179, v179
	v_fmac_f32_e32 v0, v176, v176
	v_fmac_f32_e32 v123, v178, v178
	s_waitcnt vmcnt(28)
	v_and_b32_e32 v173, 0xffff0000, v168
	v_and_b32_e32 v175, 0xffff0000, v169
	v_add_f32_e32 v0, v0, v123
	v_lshlrev_b32_e32 v171, 16, v168
	v_lshlrev_b32_e32 v174, 16, v169
	v_mul_f32_e32 v123, v173, v173
	v_mul_f32_e32 v168, v175, v175
	v_fmac_f32_e32 v123, v171, v171
	v_fmac_f32_e32 v168, v174, v174
	v_add_f32_e32 v123, v123, v168
	s_waitcnt vmcnt(26)
	v_and_b32_e32 v169, 0xffff0000, v166
	v_lshlrev_b32_e32 v170, 16, v167
	v_and_b32_e32 v167, 0xffff0000, v167
	v_add_f32_e32 v0, v0, v123
	v_lshlrev_b32_e32 v168, 16, v166
	v_mul_f32_e32 v123, v169, v169
	v_mul_f32_e32 v166, v167, v167
	v_fmac_f32_e32 v123, v168, v168
	v_fmac_f32_e32 v166, v170, v170
	v_add_f32_e32 v123, v123, v166
	v_add_f32_e32 v166, v0, v123
	s_waitcnt vmcnt(24)
	v_lshlrev_b32_e32 v0, 16, v164
	v_and_b32_e32 v123, 0xffff0000, v164
	v_lshlrev_b32_e32 v164, 16, v165
	v_and_b32_e32 v165, 0xffff0000, v165
	v_mul_f32_e32 v180, v123, v123
	v_mul_f32_e32 v181, v165, v165
	v_fmac_f32_e32 v180, v0, v0
	v_fmac_f32_e32 v181, v164, v164
	v_add_f32_e32 v180, v180, v181
	v_add_f32_e32 v166, v166, v180
	s_nop 1
	v_add_f32_dpp v166, v166, v166 quad_perm:[1,0,3,2] row_mask:0xf bank_mask:0xf bound_ctrl:1
	s_nop 1
	v_add_f32_dpp v166, v166, v166 quad_perm:[2,3,0,1] row_mask:0xf bank_mask:0xf bound_ctrl:1
	s_nop 1
	v_add_f32_dpp v166, v166, v166 row_half_mirror row_mask:0xf bank_mask:0xf bound_ctrl:1
	s_nop 1
	v_add_f32_dpp v166, v166, v166 row_mirror row_mask:0xf bank_mask:0xf bound_ctrl:1
	s_nop 0
	v_readlane_b32 s1, v166, 16
	v_readlane_b32 s6, v166, 48
	v_readlane_b32 s0, v166, 0
	v_readlane_b32 s2, v166, 32
	v_mov_b32_e32 v166, s1
	v_mov_b32_e32 v180, s6
	v_add_f32_e32 v166, s0, v166
	v_add_f32_e32 v180, s2, v180
	v_add_f32_e32 v166, v166, v180
	v_fmamk_f32 v166, v166, 0x3a800000, v188
	v_cmp_gt_f32_e32 vcc, s49, v166
	v_mul_f32_e32 v180, 0x4f800000, v166
	s_nop 0
	v_cndmask_b32_e32 v166, v166, v180, vcc
	v_sqrt_f32_e32 v180, v166
	s_nop 0
	v_add_u32_e32 v181, -1, v180
	v_fma_f32 v182, -v181, v180, v166
	v_cmp_ge_f32_e64 s[0:1], 0, v182
	v_add_u32_e32 v182, 1, v180
	s_nop 0
	v_cndmask_b32_e64 v181, v180, v181, s[0:1]
	v_fma_f32 v180, -v182, v180, v166
	v_cmp_lt_f32_e64 s[0:1], 0, v180
	s_nop 1
	v_cndmask_b32_e64 v180, v181, v182, s[0:1]
	v_mul_f32_e32 v181, 0x37800000, v180
	v_cndmask_b32_e32 v180, v180, v181, vcc
	v_cmp_class_f32_e32 vcc, v166, v189
	s_nop 1
	v_cndmask_b32_e32 v166, v180, v166, vcc
	v_div_scale_f32 v180, s[0:1], v166, v166, 1.0
	v_rcp_f32_e32 v181, v180
	s_nop 0
	v_fma_f32 v182, -v180, v181, 1.0
	v_fmac_f32_e32 v181, v182, v181
	v_div_scale_f32 v182, vcc, 1.0, v166, 1.0
	v_mul_f32_e32 v183, v182, v181
	v_fma_f32 v184, -v180, v183, v182
	v_fmac_f32_e32 v183, v184, v181
	v_fma_f32 v180, -v180, v183, v182
	v_div_fmas_f32 v180, v180, v181, v183
	v_div_fixup_f32 v166, v180, v166, 1.0
	v_mul_f32_e32 v177, v177, v166
	v_mul_f32_e32 v179, v179, v166
	v_mul_f32_e32 v173, v173, v166
	v_mul_f32_e32 v175, v175, v166
	v_mul_f32_e32 v176, v176, v166
	v_mul_f32_e32 v178, v178, v166
	v_fma_f32 v113, v3, v179, v113
	v_fma_f32 v111, v5, v177, v111
	v_mul_f32_e32 v171, v171, v166
	v_mul_f32_e32 v174, v174, v166
	v_fma_f32 v109, v15, v175, v109
	v_fma_f32 v107, v17, v173, v107
	v_mul_f32_e32 v169, v169, v166
	v_mul_f32_e32 v167, v167, v166
	v_fma_f32 v112, v2, v178, v112
	v_fmac_f32_e32 v110, v4, v176
	v_mul_f32_e32 v176, v111, v111
	v_mul_f32_e32 v177, v113, v113
	v_fma_f32 v108, v14, v174, v108
	v_fmac_f32_e32 v106, v16, v171
	v_mul_f32_e32 v171, v107, v107
	v_mul_f32_e32 v173, v109, v109
	v_mul_f32_e32 v168, v168, v166
	v_mul_f32_e32 v170, v170, v166
	v_fma_f32 v105, v27, v167, v105
	v_fma_f32 v103, v29, v169, v103
	v_mul_f32_e32 v123, v123, v166
	v_mul_f32_e32 v165, v165, v166
	v_fmac_f32_e32 v176, v110, v110
	v_fmac_f32_e32 v177, v112, v112
	v_fmac_f32_e32 v171, v106, v106
	v_fmac_f32_e32 v173, v108, v108
	v_fma_f32 v104, v26, v170, v104
	v_fmac_f32_e32 v102, v28, v168
	v_mul_f32_e32 v167, v103, v103
	v_mul_f32_e32 v168, v105, v105
	v_mul_f32_e32 v0, v0, v166
	v_mul_f32_e32 v164, v164, v166
	v_fma_f32 v101, v39, v165, v101
	v_fma_f32 v99, v41, v123, v99
	v_add_f32_e32 v176, v176, v177
	v_add_f32_e32 v171, v171, v173
	v_fmac_f32_e32 v167, v102, v102
	v_fmac_f32_e32 v168, v104, v104
	v_fma_f32 v100, v38, v164, v100
	v_fmac_f32_e32 v98, v40, v0
	v_mul_f32_e32 v0, v99, v99
	v_mul_f32_e32 v123, v101, v101
	v_add_f32_e32 v171, v176, v171
	v_add_f32_e32 v167, v167, v168
	v_fmac_f32_e32 v0, v98, v98
	v_fmac_f32_e32 v123, v100, v100
	v_add_f32_e32 v167, v167, v171
	v_add_f32_e32 v0, v0, v123
	v_add_f32_e32 v0, v0, v167
	s_nop 1
	s_nop 1
	v_add_f32_dpp v0, v0, v0 quad_perm:[1,0,3,2] row_mask:0xf bank_mask:0xf bound_ctrl:1
	s_nop 1
	s_nop 1
	v_add_f32_dpp v0, v0, v0 quad_perm:[2,3,0,1] row_mask:0xf bank_mask:0xf bound_ctrl:1
	s_nop 1
	v_add_f32_dpp v0, v0, v0 row_half_mirror row_mask:0xf bank_mask:0xf bound_ctrl:1
	s_nop 1
	v_add_f32_dpp v0, v0, v0 row_mirror row_mask:0xf bank_mask:0xf bound_ctrl:1
	s_nop 0
	v_readlane_b32 s1, v0, 16
	v_readlane_b32 s6, v0, 48
	v_readlane_b32 s0, v0, 0
	v_readlane_b32 s2, v0, 32
	v_mov_b32_e32 v0, s1
	v_mov_b32_e32 v123, s6
	v_add_f32_e32 v0, s0, v0
	v_add_f32_e32 v123, s2, v123
	v_add_f32_e32 v0, v0, v123
	v_fmamk_f32 v0, v0, 0x3a800000, v188
	v_cmp_gt_f32_e32 vcc, s49, v0
	v_mul_f32_e32 v123, 0x4f800000, v0
	s_nop 0
	v_cndmask_b32_e32 v0, v0, v123, vcc
	v_sqrt_f32_e32 v123, v0
	s_nop 0
	v_add_u32_e32 v162, -1, v123
	v_fma_f32 v163, -v162, v123, v0
	v_cmp_ge_f32_e64 s[0:1], 0, v163
	v_add_u32_e32 v163, 1, v123
	s_nop 0
	v_cndmask_b32_e64 v162, v123, v162, s[0:1]
	v_fma_f32 v123, -v163, v123, v0
	v_cmp_lt_f32_e64 s[0:1], 0, v123
	s_nop 1
	v_cndmask_b32_e64 v123, v162, v163, s[0:1]
	v_mul_f32_e32 v162, 0x37800000, v123
	v_cndmask_b32_e32 v123, v123, v162, vcc
	v_cmp_class_f32_e32 vcc, v0, v189
	s_nop 1
	v_cndmask_b32_e32 v0, v123, v0, vcc
	v_div_scale_f32 v123, s[0:1], v0, v0, 1.0
	v_rcp_f32_e32 v162, v123
	s_nop 0
	v_fma_f32 v163, -v123, v162, 1.0
	v_fmac_f32_e32 v162, v163, v162
	v_div_scale_f32 v163, vcc, 1.0, v0, 1.0
	v_mul_f32_e32 v164, v163, v162
	v_fma_f32 v165, -v123, v164, v163
	v_fmac_f32_e32 v164, v165, v162
	v_fma_f32 v123, -v123, v164, v163
	v_div_fmas_f32 v123, v123, v162, v164
	v_div_fixup_f32 v0, v123, v0, 1.0
	v_mul_f32_e32 v111, v111, v0
	v_mul_f32_e32 v110, v110, v0
	v_mul_f32_e32 v107, v107, v0
	v_mul_f32_e32 v106, v106, v0
	v_mul_f32_e32 v103, v103, v0
	v_mul_f32_e32 v102, v102, v0
	v_mul_f32_e32 v98, v98, v0
	v_mul_f32_e32 v113, v113, v0
	v_mul_f32_e32 v112, v112, v0
	v_fma_f32 v110, v8, v110, v10
	v_fma_f32 v111, v9, v111, v11
	v_mul_f32_e32 v109, v109, v0
	v_mul_f32_e32 v108, v108, v0
	v_fma_f32 v106, v20, v106, v22
	v_fma_f32 v107, v21, v107, v23
	v_mul_f32_e32 v105, v105, v0
	v_mul_f32_e32 v104, v104, v0
	v_fma_f32 v102, v32, v102, v34
	v_fma_f32 v103, v33, v103, v35
	v_mul_f32_e32 v99, v99, v0
	v_mul_f32_e32 v101, v101, v0
	v_fma_f32 v98, v44, v98, v46
	v_fma_f32 v112, v6, v112, v12
	v_fma_f32 v113, v7, v113, v13
	v_cvt_pk_bf16_f32 v110, v110, v111
	v_cvt_pk_bf16_f32 v111, v112, v113
	global_store_dwordx2 v[160:161], v[110:111], off
	v_fma_f32 v108, v18, v108, v24
	v_fma_f32 v109, v19, v109, v25
	v_cvt_pk_bf16_f32 v106, v106, v107
	v_cvt_pk_bf16_f32 v107, v108, v109
	global_store_dwordx2 v[160:161], v[106:107], off offset:512
	v_fma_f32 v104, v30, v104, v36
	v_fma_f32 v105, v31, v105, v37
	v_cvt_pk_bf16_f32 v102, v102, v103
	v_cvt_pk_bf16_f32 v103, v104, v105
	global_store_dwordx2 v[160:161], v[102:103], off offset:1024
	v_mul_f32_e32 v0, v100, v0
	v_fma_f32 v100, v43, v101, v49
	v_fma_f32 v99, v45, v99, v47
	v_cvt_pk_bf16_f32 v98, v98, v99
	v_fma_f32 v0, v42, v0, v48
	v_cvt_pk_bf16_f32 v99, v0, v100
	global_store_dwordx2 v[160:161], v[98:99], off offset:1536
	s_waitcnt vmcnt(26)
	v_and_b32_e32 v98, 0xffff0000, v158
	v_and_b32_e32 v100, 0xffff0000, v159
	v_lshlrev_b32_e32 v0, 16, v158
	v_lshlrev_b32_e32 v99, 16, v159
	v_mul_f32_e32 v101, v98, v98
	v_mul_f32_e32 v102, v100, v100
	v_fmac_f32_e32 v101, v0, v0
	v_fmac_f32_e32 v102, v99, v99
	s_waitcnt vmcnt(24)
	v_and_b32_e32 v103, 0xffff0000, v156
	v_and_b32_e32 v105, 0xffff0000, v157
	v_add_f32_e32 v101, v101, v102
	v_lshlrev_b32_e32 v102, 16, v156
	v_lshlrev_b32_e32 v104, 16, v157
	v_mul_f32_e32 v106, v103, v103
	v_mul_f32_e32 v107, v105, v105
	v_fmac_f32_e32 v106, v102, v102
	v_fmac_f32_e32 v107, v104, v104
	v_add_f32_e32 v106, v106, v107
	s_waitcnt vmcnt(22)
	v_and_b32_e32 v107, 0xffff0000, v154
	v_and_b32_e32 v109, 0xffff0000, v155
	v_add_f32_e32 v101, v101, v106
	v_lshlrev_b32_e32 v106, 16, v154
	v_lshlrev_b32_e32 v108, 16, v155
	v_mul_f32_e32 v110, v107, v107
	v_mul_f32_e32 v111, v109, v109
	v_fmac_f32_e32 v110, v106, v106
	v_fmac_f32_e32 v111, v108, v108
	v_add_f32_e32 v110, v110, v111
	s_waitcnt vmcnt(20)
	v_and_b32_e32 v111, 0xffff0000, v152
	v_and_b32_e32 v113, 0xffff0000, v153
	v_add_f32_e32 v101, v101, v110
	v_lshlrev_b32_e32 v110, 16, v152
	v_lshlrev_b32_e32 v112, 16, v153
	v_mul_f32_e32 v123, v111, v111
	v_mul_f32_e32 v152, v113, v113
	v_fmac_f32_e32 v123, v110, v110
	v_fmac_f32_e32 v152, v112, v112
	v_add_f32_e32 v123, v123, v152
	v_add_f32_e32 v101, v101, v123
	s_nop 1
	v_add_f32_dpp v101, v101, v101 quad_perm:[1,0,3,2] row_mask:0xf bank_mask:0xf bound_ctrl:1
	s_nop 1
	v_add_f32_dpp v101, v101, v101 quad_perm:[2,3,0,1] row_mask:0xf bank_mask:0xf bound_ctrl:1
	s_nop 1
	v_add_f32_dpp v101, v101, v101 row_half_mirror row_mask:0xf bank_mask:0xf bound_ctrl:1
	s_nop 1
	v_add_f32_dpp v101, v101, v101 row_mirror row_mask:0xf bank_mask:0xf bound_ctrl:1
	s_nop 0
	v_readlane_b32 s1, v101, 16
	v_readlane_b32 s6, v101, 48
	v_readlane_b32 s0, v101, 0
	v_readlane_b32 s2, v101, 32
	v_mov_b32_e32 v101, s1
	v_mov_b32_e32 v123, s6
	v_add_f32_e32 v101, s0, v101
	v_add_f32_e32 v123, s2, v123
	v_add_f32_e32 v101, v101, v123
	v_fmamk_f32 v101, v101, 0x3a800000, v188
	v_cmp_gt_f32_e32 vcc, s49, v101
	v_mul_f32_e32 v123, 0x4f800000, v101
	s_nop 0
	v_cndmask_b32_e32 v101, v101, v123, vcc
	v_sqrt_f32_e32 v123, v101
	s_nop 0
	v_add_u32_e32 v152, -1, v123
	v_fma_f32 v153, -v152, v123, v101
	v_cmp_ge_f32_e64 s[0:1], 0, v153
	v_add_u32_e32 v153, 1, v123
	s_nop 0
	v_cndmask_b32_e64 v152, v123, v152, s[0:1]
	v_fma_f32 v123, -v153, v123, v101
	v_cmp_lt_f32_e64 s[0:1], 0, v123
	s_nop 1
	v_cndmask_b32_e64 v123, v152, v153, s[0:1]
	v_mul_f32_e32 v152, 0x37800000, v123
	v_cndmask_b32_e32 v123, v123, v152, vcc
	v_cmp_class_f32_e32 vcc, v101, v189
	s_nop 1
	v_cndmask_b32_e32 v101, v123, v101, vcc
	v_div_scale_f32 v123, s[0:1], v101, v101, 1.0
	v_rcp_f32_e32 v152, v123
	s_nop 0
	v_fma_f32 v153, -v123, v152, 1.0
	v_fmac_f32_e32 v152, v153, v152
	v_div_scale_f32 v153, vcc, 1.0, v101, 1.0
	v_mul_f32_e32 v154, v153, v152
	v_fma_f32 v155, -v123, v154, v153
	v_fmac_f32_e32 v154, v155, v152
	v_fma_f32 v123, -v123, v154, v153
	v_div_fmas_f32 v123, v123, v152, v154
	v_div_fixup_f32 v101, v123, v101, 1.0
	v_mul_f32_e32 v98, v98, v101
	v_mul_f32_e32 v100, v100, v101
	v_mul_f32_e32 v0, v0, v101
	v_mul_f32_e32 v99, v99, v101
	v_fma_f32 v97, v3, v100, v97
	v_fma_f32 v95, v5, v98, v95
	v_fma_f32 v96, v2, v99, v96
	v_fmac_f32_e32 v94, v4, v0
	v_mul_f32_e32 v0, v95, v95
	v_mul_f32_e32 v100, v97, v97
	v_fmac_f32_e32 v0, v94, v94
	v_fmac_f32_e32 v100, v96, v96
	v_add_f32_e32 v0, v0, v100
	v_mul_f32_e32 v100, v102, v101
	v_mul_f32_e32 v102, v103, v101
	v_mul_f32_e32 v103, v104, v101
	v_mul_f32_e32 v104, v105, v101
	v_fma_f32 v93, v15, v104, v93
	v_fma_f32 v91, v17, v102, v91
	v_fma_f32 v92, v14, v103, v92
	v_fmac_f32_e32 v90, v16, v100
	v_mul_f32_e32 v100, v91, v91
	v_mul_f32_e32 v102, v93, v93
	v_fmac_f32_e32 v100, v90, v90
	v_fmac_f32_e32 v102, v92, v92
	v_add_f32_e32 v100, v100, v102
	v_mul_f32_e32 v102, v107, v101
	v_mul_f32_e32 v104, v109, v101
	v_add_f32_e32 v0, v0, v100
	v_mul_f32_e32 v100, v106, v101
	v_mul_f32_e32 v103, v108, v101
	v_fma_f32 v89, v27, v104, v89
	v_fma_f32 v87, v29, v102, v87
	v_fma_f32 v88, v26, v103, v88
	v_fmac_f32_e32 v86, v28, v100
	v_mul_f32_e32 v100, v87, v87
	v_mul_f32_e32 v102, v89, v89
	v_fmac_f32_e32 v100, v86, v86
	v_fmac_f32_e32 v102, v88, v88
	v_add_f32_e32 v100, v100, v102
	v_add_f32_e32 v0, v100, v0
	v_mul_f32_e32 v100, v110, v101
	v_mul_f32_e32 v102, v111, v101
	v_mul_f32_e32 v103, v112, v101
	v_mul_f32_e32 v101, v113, v101
	v_lshl_add_u64 v[98:99], v[120:121], 0, v[150:151]
	v_fma_f32 v85, v39, v101, v85
	v_fma_f32 v84, v38, v103, v84
	v_fma_f32 v83, v41, v102, v83
	v_fmac_f32_e32 v82, v40, v100
	s_nop 1
	s_nop 1
	s_nop 1
	s_nop 1
	v_mul_f32_e32 v98, v83, v83
	v_mul_f32_e32 v99, v85, v85
	v_fmac_f32_e32 v98, v82, v82
	v_fmac_f32_e32 v99, v84, v84
	v_add_f32_e32 v98, v98, v99
	v_add_f32_e32 v0, v98, v0
	s_nop 1
	v_add_f32_dpp v0, v0, v0 quad_perm:[1,0,3,2] row_mask:0xf bank_mask:0xf bound_ctrl:1
	s_nop 1
	v_add_f32_dpp v0, v0, v0 quad_perm:[2,3,0,1] row_mask:0xf bank_mask:0xf bound_ctrl:1
	s_nop 1
	v_add_f32_dpp v0, v0, v0 row_half_mirror row_mask:0xf bank_mask:0xf bound_ctrl:1
	s_nop 1
	v_add_f32_dpp v0, v0, v0 row_mirror row_mask:0xf bank_mask:0xf bound_ctrl:1
	s_nop 0
	v_readlane_b32 s1, v0, 16
	v_readlane_b32 s6, v0, 48
	v_readlane_b32 s0, v0, 0
	v_readlane_b32 s2, v0, 32
	v_mov_b32_e32 v0, s1
	v_mov_b32_e32 v98, s6
	v_add_f32_e32 v0, s0, v0
	v_add_f32_e32 v98, s2, v98
	v_add_f32_e32 v0, v0, v98
	v_fmamk_f32 v0, v0, 0x3a800000, v188
	v_cmp_gt_f32_e32 vcc, s49, v0
	v_mul_f32_e32 v98, 0x4f800000, v0
	s_nop 0
	v_cndmask_b32_e32 v0, v0, v98, vcc
	v_sqrt_f32_e32 v98, v0
	s_nop 0
	v_add_u32_e32 v99, -1, v98
	v_fma_f32 v100, -v99, v98, v0
	v_cmp_ge_f32_e64 s[0:1], 0, v100
	v_add_u32_e32 v100, 1, v98
	s_nop 0
	v_cndmask_b32_e64 v99, v98, v99, s[0:1]
	v_fma_f32 v98, -v100, v98, v0
	v_cmp_lt_f32_e64 s[0:1], 0, v98
	s_nop 1
	v_cndmask_b32_e64 v98, v99, v100, s[0:1]
	v_mul_f32_e32 v99, 0x37800000, v98
	v_cndmask_b32_e32 v98, v98, v99, vcc
	v_cmp_class_f32_e32 vcc, v0, v189
	s_nop 1
	v_cndmask_b32_e32 v0, v98, v0, vcc
	v_div_scale_f32 v98, s[0:1], v0, v0, 1.0
	v_rcp_f32_e32 v99, v98
	s_nop 0
	v_fma_f32 v100, -v98, v99, 1.0
	v_fmac_f32_e32 v99, v100, v99
	v_div_scale_f32 v100, vcc, 1.0, v0, 1.0
	v_mul_f32_e32 v101, v100, v99
	v_fma_f32 v102, -v98, v101, v100
	v_fmac_f32_e32 v101, v102, v99
	v_fma_f32 v98, -v98, v101, v100
	v_div_fmas_f32 v98, v98, v99, v101
	v_div_fixup_f32 v0, v98, v0, 1.0
	v_mul_f32_e32 v95, v95, v0
	v_mul_f32_e32 v94, v94, v0
	v_mul_f32_e32 v91, v91, v0
	v_mul_f32_e32 v90, v90, v0
	v_mul_f32_e32 v87, v87, v0
	v_mul_f32_e32 v86, v86, v0
	v_mul_f32_e32 v82, v82, v0
	v_lshl_add_u64 v[98:99], v[118:119], 0, v[140:141]
	v_mul_f32_e32 v97, v97, v0
	v_mul_f32_e32 v96, v96, v0
	v_fma_f32 v94, v8, v94, v10
	v_fma_f32 v95, v9, v95, v11
	v_mul_f32_e32 v93, v93, v0
	v_mul_f32_e32 v92, v92, v0
	v_fma_f32 v90, v20, v90, v22
	v_fma_f32 v91, v21, v91, v23
	v_mul_f32_e32 v89, v89, v0
	v_mul_f32_e32 v88, v88, v0
	v_fma_f32 v86, v32, v86, v34
	v_fma_f32 v87, v33, v87, v35
	v_mul_f32_e32 v83, v83, v0
	v_mul_f32_e32 v85, v85, v0
	v_fma_f32 v82, v44, v82, v46
	v_fma_f32 v96, v6, v96, v12
	v_fma_f32 v97, v7, v97, v13
	v_cvt_pk_bf16_f32 v94, v94, v95
	v_cvt_pk_bf16_f32 v95, v96, v97
	global_store_dwordx2 v[98:99], v[94:95], off
	v_fma_f32 v92, v18, v92, v24
	v_fma_f32 v93, v19, v93, v25
	v_cvt_pk_bf16_f32 v90, v90, v91
	v_cvt_pk_bf16_f32 v91, v92, v93
	global_store_dwordx2 v[98:99], v[90:91], off offset:512
	v_fma_f32 v88, v30, v88, v36
	v_fma_f32 v89, v31, v89, v37
	v_cvt_pk_bf16_f32 v86, v86, v87
	v_cvt_pk_bf16_f32 v87, v88, v89
	global_store_dwordx2 v[98:99], v[86:87], off offset:1024
	v_mul_f32_e32 v0, v84, v0
	v_fma_f32 v84, v43, v85, v49
	v_fma_f32 v83, v45, v83, v47
	v_cvt_pk_bf16_f32 v82, v82, v83
	v_fma_f32 v0, v42, v0, v48
	v_cvt_pk_bf16_f32 v83, v0, v84
	global_store_dwordx2 v[98:99], v[82:83], off offset:1536
	s_waitcnt vmcnt(22)
	v_and_b32_e32 v82, 0xffff0000, v148
	v_and_b32_e32 v84, 0xffff0000, v149
	v_lshlrev_b32_e32 v0, 16, v148
	v_lshlrev_b32_e32 v83, 16, v149
	v_mul_f32_e32 v85, v82, v82
	v_mul_f32_e32 v86, v84, v84
	v_fmac_f32_e32 v85, v0, v0
	v_fmac_f32_e32 v86, v83, v83
	s_waitcnt vmcnt(20)
	v_and_b32_e32 v87, 0xffff0000, v146
	v_and_b32_e32 v89, 0xffff0000, v147
	v_add_f32_e32 v85, v85, v86
	v_lshlrev_b32_e32 v86, 16, v146
	v_lshlrev_b32_e32 v88, 16, v147
	v_mul_f32_e32 v90, v87, v87
	v_mul_f32_e32 v91, v89, v89
	v_fmac_f32_e32 v90, v86, v86
	v_fmac_f32_e32 v91, v88, v88
	v_add_f32_e32 v90, v90, v91
	s_waitcnt vmcnt(18)
	v_and_b32_e32 v91, 0xffff0000, v144
	v_and_b32_e32 v93, 0xffff0000, v145
	v_add_f32_e32 v85, v85, v90
	v_lshlrev_b32_e32 v90, 16, v144
	v_lshlrev_b32_e32 v92, 16, v145
	v_mul_f32_e32 v94, v91, v91
	v_mul_f32_e32 v95, v93, v93
	v_fmac_f32_e32 v94, v90, v90
	v_fmac_f32_e32 v95, v92, v92
	v_add_f32_e32 v94, v94, v95
	s_waitcnt vmcnt(16)
	v_and_b32_e32 v95, 0xffff0000, v142
	v_and_b32_e32 v97, 0xffff0000, v143
	v_add_f32_e32 v85, v85, v94
	v_lshlrev_b32_e32 v94, 16, v142
	v_lshlrev_b32_e32 v96, 16, v143
	v_mul_f32_e32 v98, v95, v95
	v_mul_f32_e32 v99, v97, v97
	v_fmac_f32_e32 v98, v94, v94
	v_fmac_f32_e32 v99, v96, v96
	v_add_f32_e32 v98, v98, v99
	v_add_f32_e32 v85, v85, v98
	s_nop 1
	v_add_f32_dpp v85, v85, v85 quad_perm:[1,0,3,2] row_mask:0xf bank_mask:0xf bound_ctrl:1
	s_nop 1
	v_add_f32_dpp v85, v85, v85 quad_perm:[2,3,0,1] row_mask:0xf bank_mask:0xf bound_ctrl:1
	s_nop 1
	v_add_f32_dpp v85, v85, v85 row_half_mirror row_mask:0xf bank_mask:0xf bound_ctrl:1
	s_nop 1
	v_add_f32_dpp v85, v85, v85 row_mirror row_mask:0xf bank_mask:0xf bound_ctrl:1
	s_nop 0
	v_readlane_b32 s1, v85, 16
	v_readlane_b32 s6, v85, 48
	v_readlane_b32 s0, v85, 0
	v_readlane_b32 s2, v85, 32
	v_mov_b32_e32 v85, s1
	v_mov_b32_e32 v98, s6
	v_add_f32_e32 v85, s0, v85
	v_add_f32_e32 v98, s2, v98
	v_add_f32_e32 v85, v85, v98
	v_fmamk_f32 v85, v85, 0x3a800000, v188
	v_cmp_gt_f32_e32 vcc, s49, v85
	v_mul_f32_e32 v98, 0x4f800000, v85
	s_nop 0
	v_cndmask_b32_e32 v85, v85, v98, vcc
	v_sqrt_f32_e32 v98, v85
	s_nop 0
	v_add_u32_e32 v99, -1, v98
	v_fma_f32 v100, -v99, v98, v85
	v_cmp_ge_f32_e64 s[0:1], 0, v100
	v_add_u32_e32 v100, 1, v98
	s_nop 0
	v_cndmask_b32_e64 v99, v98, v99, s[0:1]
	v_fma_f32 v98, -v100, v98, v85
	v_cmp_lt_f32_e64 s[0:1], 0, v98
	s_nop 1
	v_cndmask_b32_e64 v98, v99, v100, s[0:1]
	v_mul_f32_e32 v99, 0x37800000, v98
	v_cndmask_b32_e32 v98, v98, v99, vcc
	v_cmp_class_f32_e32 vcc, v85, v189
	s_nop 1
	v_cndmask_b32_e32 v85, v98, v85, vcc
	v_div_scale_f32 v98, s[0:1], v85, v85, 1.0
	v_rcp_f32_e32 v99, v98
	s_nop 0
	v_fma_f32 v100, -v98, v99, 1.0
	v_fmac_f32_e32 v99, v100, v99
	v_div_scale_f32 v100, vcc, 1.0, v85, 1.0
	v_mul_f32_e32 v101, v100, v99
	v_fma_f32 v102, -v98, v101, v100
	v_fmac_f32_e32 v101, v102, v99
	v_fma_f32 v98, -v98, v101, v100
	v_div_fmas_f32 v98, v98, v99, v101
	v_div_fixup_f32 v85, v98, v85, 1.0
	v_mul_f32_e32 v82, v82, v85
	v_mul_f32_e32 v84, v84, v85
	v_mul_f32_e32 v0, v0, v85
	v_mul_f32_e32 v83, v83, v85
	v_fma_f32 v81, v3, v84, v81
	v_fma_f32 v79, v5, v82, v79
	v_fma_f32 v80, v2, v83, v80
	v_fmac_f32_e32 v78, v4, v0
	v_mul_f32_e32 v0, v79, v79
	v_mul_f32_e32 v84, v81, v81
	v_fmac_f32_e32 v0, v78, v78
	v_fmac_f32_e32 v84, v80, v80
	v_add_f32_e32 v0, v0, v84
	v_mul_f32_e32 v84, v86, v85
	v_mul_f32_e32 v86, v87, v85
	v_mul_f32_e32 v87, v88, v85
	v_mul_f32_e32 v88, v89, v85
	v_fma_f32 v77, v15, v88, v77
	v_fma_f32 v75, v17, v86, v75
	v_fma_f32 v76, v14, v87, v76
	v_fmac_f32_e32 v74, v16, v84
	v_mul_f32_e32 v84, v75, v75
	v_mul_f32_e32 v86, v77, v77
	v_fmac_f32_e32 v84, v74, v74
	v_fmac_f32_e32 v86, v76, v76
	v_add_f32_e32 v84, v84, v86
	v_mul_f32_e32 v86, v91, v85
	v_mul_f32_e32 v88, v93, v85
	v_add_f32_e32 v0, v0, v84
	v_mul_f32_e32 v84, v90, v85
	v_mul_f32_e32 v87, v92, v85
	v_fma_f32 v73, v27, v88, v73
	v_fma_f32 v71, v29, v86, v71
	v_fma_f32 v72, v26, v87, v72
	v_fmac_f32_e32 v70, v28, v84
	v_mul_f32_e32 v84, v71, v71
	v_mul_f32_e32 v86, v73, v73
	v_fmac_f32_e32 v84, v70, v70
	v_fmac_f32_e32 v86, v72, v72
	v_add_f32_e32 v84, v84, v86
	v_add_f32_e32 v0, v84, v0
	v_mul_f32_e32 v84, v94, v85
	v_mul_f32_e32 v86, v95, v85
	v_mul_f32_e32 v87, v96, v85
	v_mul_f32_e32 v85, v97, v85
	v_lshl_add_u64 v[82:83], v[120:121], 0, v[138:139]
	v_fma_f32 v69, v39, v85, v69
	v_fma_f32 v68, v38, v87, v68
	v_fma_f32 v67, v41, v86, v67
	v_fmac_f32_e32 v66, v40, v84
	s_nop 1
	s_nop 1
	s_nop 1
	s_nop 1
	v_mul_f32_e32 v82, v67, v67
	v_mul_f32_e32 v83, v69, v69
	v_fmac_f32_e32 v82, v66, v66
	v_fmac_f32_e32 v83, v68, v68
	v_add_f32_e32 v82, v82, v83
	v_add_f32_e32 v0, v82, v0
	s_nop 1
	v_add_f32_dpp v0, v0, v0 quad_perm:[1,0,3,2] row_mask:0xf bank_mask:0xf bound_ctrl:1
	s_nop 1
	v_add_f32_dpp v0, v0, v0 quad_perm:[2,3,0,1] row_mask:0xf bank_mask:0xf bound_ctrl:1
	s_nop 1
	v_add_f32_dpp v0, v0, v0 row_half_mirror row_mask:0xf bank_mask:0xf bound_ctrl:1
	s_nop 1
	v_add_f32_dpp v0, v0, v0 row_mirror row_mask:0xf bank_mask:0xf bound_ctrl:1
	s_nop 0
	v_readlane_b32 s1, v0, 16
	v_readlane_b32 s6, v0, 48
	v_readlane_b32 s0, v0, 0
	v_readlane_b32 s2, v0, 32
	v_mov_b32_e32 v0, s1
	v_mov_b32_e32 v82, s6
	v_add_f32_e32 v0, s0, v0
	v_add_f32_e32 v82, s2, v82
	v_add_f32_e32 v0, v0, v82
	v_fmamk_f32 v0, v0, 0x3a800000, v188
	v_cmp_gt_f32_e32 vcc, s49, v0
	v_mul_f32_e32 v82, 0x4f800000, v0
	s_nop 0
	v_cndmask_b32_e32 v0, v0, v82, vcc
	v_sqrt_f32_e32 v82, v0
	s_nop 0
	v_add_u32_e32 v83, -1, v82
	v_fma_f32 v84, -v83, v82, v0
	v_cmp_ge_f32_e64 s[0:1], 0, v84
	v_add_u32_e32 v84, 1, v82
	s_nop 0
	v_cndmask_b32_e64 v83, v82, v83, s[0:1]
	v_fma_f32 v82, -v84, v82, v0
	v_cmp_lt_f32_e64 s[0:1], 0, v82
	s_nop 1
	v_cndmask_b32_e64 v82, v83, v84, s[0:1]
	v_mul_f32_e32 v83, 0x37800000, v82
	v_cndmask_b32_e32 v82, v82, v83, vcc
	v_cmp_class_f32_e32 vcc, v0, v189
	s_nop 1
	v_cndmask_b32_e32 v0, v82, v0, vcc
	v_div_scale_f32 v82, s[0:1], v0, v0, 1.0
	v_rcp_f32_e32 v83, v82
	s_nop 0
	v_fma_f32 v84, -v82, v83, 1.0
	v_fmac_f32_e32 v83, v84, v83
	v_div_scale_f32 v84, vcc, 1.0, v0, 1.0
	v_mul_f32_e32 v85, v84, v83
	v_fma_f32 v86, -v82, v85, v84
	v_fmac_f32_e32 v85, v86, v83
	v_fma_f32 v82, -v82, v85, v84
	v_div_fmas_f32 v82, v82, v83, v85
	v_div_fixup_f32 v0, v82, v0, 1.0
	v_mul_f32_e32 v79, v79, v0
	v_mul_f32_e32 v78, v78, v0
	v_mul_f32_e32 v75, v75, v0
	v_mul_f32_e32 v74, v74, v0
	v_mul_f32_e32 v71, v71, v0
	v_mul_f32_e32 v70, v70, v0
	v_mul_f32_e32 v66, v66, v0
	v_lshl_add_u64 v[82:83], v[118:119], 0, v[136:137]
	v_mul_f32_e32 v81, v81, v0
	v_mul_f32_e32 v80, v80, v0
	v_fma_f32 v78, v8, v78, v10
	v_fma_f32 v79, v9, v79, v11
	v_mul_f32_e32 v77, v77, v0
	v_mul_f32_e32 v76, v76, v0
	v_fma_f32 v74, v20, v74, v22
	v_fma_f32 v75, v21, v75, v23
	v_mul_f32_e32 v73, v73, v0
	v_mul_f32_e32 v72, v72, v0
	v_fma_f32 v70, v32, v70, v34
	v_fma_f32 v71, v33, v71, v35
	v_mul_f32_e32 v67, v67, v0
	v_mul_f32_e32 v69, v69, v0
	v_fma_f32 v66, v44, v66, v46
	v_fma_f32 v80, v6, v80, v12
	v_fma_f32 v81, v7, v81, v13
	v_cvt_pk_bf16_f32 v78, v78, v79
	v_cvt_pk_bf16_f32 v79, v80, v81
	global_store_dwordx2 v[82:83], v[78:79], off
	v_fma_f32 v76, v18, v76, v24
	v_fma_f32 v77, v19, v77, v25
	v_cvt_pk_bf16_f32 v74, v74, v75
	v_cvt_pk_bf16_f32 v75, v76, v77
	global_store_dwordx2 v[82:83], v[74:75], off offset:512
	v_fma_f32 v72, v30, v72, v36
	v_fma_f32 v73, v31, v73, v37
	v_cvt_pk_bf16_f32 v70, v70, v71
	v_cvt_pk_bf16_f32 v71, v72, v73
	global_store_dwordx2 v[82:83], v[70:71], off offset:1024
	v_mul_f32_e32 v0, v68, v0
	v_fma_f32 v68, v43, v69, v49
	v_fma_f32 v67, v45, v67, v47
	v_cvt_pk_bf16_f32 v66, v66, v67
	v_fma_f32 v0, v42, v0, v48
	v_cvt_pk_bf16_f32 v67, v0, v68
	global_store_dwordx2 v[82:83], v[66:67], off offset:1536
	s_waitcnt vmcnt(18)
	v_and_b32_e32 v66, 0xffff0000, v134
	v_and_b32_e32 v68, 0xffff0000, v135
	v_lshlrev_b32_e32 v0, 16, v134
	v_lshlrev_b32_e32 v67, 16, v135
	v_mul_f32_e32 v69, v66, v66
	v_mul_f32_e32 v70, v68, v68
	v_fmac_f32_e32 v69, v0, v0
	v_fmac_f32_e32 v70, v67, v67
	v_add_f32_e32 v73, v69, v70
	s_waitcnt vmcnt(16)
	v_and_b32_e32 v70, 0xffff0000, v132
	v_and_b32_e32 v72, 0xffff0000, v133
	v_lshlrev_b32_e32 v69, 16, v132
	v_lshlrev_b32_e32 v71, 16, v133
	v_mul_f32_e32 v74, v70, v70
	v_mul_f32_e32 v75, v72, v72
	v_fmac_f32_e32 v74, v69, v69
	v_fmac_f32_e32 v75, v71, v71
	v_add_f32_e32 v74, v74, v75
	v_add_f32_e32 v77, v73, v74
	s_waitcnt vmcnt(14)
	v_and_b32_e32 v74, 0xffff0000, v130
	v_and_b32_e32 v76, 0xffff0000, v131
	v_lshlrev_b32_e32 v73, 16, v130
	v_lshlrev_b32_e32 v75, 16, v131
	v_mul_f32_e32 v78, v74, v74
	v_mul_f32_e32 v79, v76, v76
	v_fmac_f32_e32 v78, v73, v73
	v_fmac_f32_e32 v79, v75, v75
	v_add_f32_e32 v78, v78, v79
	v_add_f32_e32 v81, v77, v78
	s_waitcnt vmcnt(12)
	v_and_b32_e32 v78, 0xffff0000, v128
	v_and_b32_e32 v80, 0xffff0000, v129
	v_lshlrev_b32_e32 v77, 16, v128
	v_lshlrev_b32_e32 v79, 16, v129
	v_mul_f32_e32 v82, v78, v78
	v_mul_f32_e32 v83, v80, v80
	v_fmac_f32_e32 v82, v77, v77
	v_fmac_f32_e32 v83, v79, v79
	v_add_f32_e32 v82, v82, v83
	v_add_f32_e32 v81, v81, v82
	s_nop 1
	v_add_f32_dpp v81, v81, v81 quad_perm:[1,0,3,2] row_mask:0xf bank_mask:0xf bound_ctrl:1
	s_nop 1
	v_add_f32_dpp v81, v81, v81 quad_perm:[2,3,0,1] row_mask:0xf bank_mask:0xf bound_ctrl:1
	s_nop 1
	v_add_f32_dpp v81, v81, v81 row_half_mirror row_mask:0xf bank_mask:0xf bound_ctrl:1
	s_nop 1
	v_add_f32_dpp v81, v81, v81 row_mirror row_mask:0xf bank_mask:0xf bound_ctrl:1
	s_nop 0
	v_readlane_b32 s6, v81, 16
	v_readlane_b32 s1, v81, 48
	v_readlane_b32 s2, v81, 0
	v_readlane_b32 s0, v81, 32
	v_mov_b32_e32 v81, s6
	v_mov_b32_e32 v82, s1
	v_add_f32_e32 v81, s2, v81
	v_add_f32_e32 v82, s0, v82
	v_add_f32_e32 v81, v81, v82
	v_fmamk_f32 v81, v81, 0x3a800000, v188
	v_cmp_gt_f32_e32 vcc, s49, v81
	v_mul_f32_e32 v82, 0x4f800000, v81
	s_nop 0
	v_cndmask_b32_e32 v81, v81, v82, vcc
	v_sqrt_f32_e32 v82, v81
	s_nop 0
	v_add_u32_e32 v83, -1, v82
	v_fma_f32 v84, -v83, v82, v81
	v_cmp_ge_f32_e64 s[0:1], 0, v84
	v_add_u32_e32 v84, 1, v82
	s_nop 0
	v_cndmask_b32_e64 v83, v82, v83, s[0:1]
	v_fma_f32 v82, -v84, v82, v81
	v_cmp_lt_f32_e64 s[0:1], 0, v82
	s_nop 1
	v_cndmask_b32_e64 v82, v83, v84, s[0:1]
	v_mul_f32_e32 v83, 0x37800000, v82
	v_cndmask_b32_e32 v82, v82, v83, vcc
	v_cmp_class_f32_e32 vcc, v81, v189
	s_nop 1
	v_cndmask_b32_e32 v81, v82, v81, vcc
	v_div_scale_f32 v82, s[0:1], v81, v81, 1.0
	v_rcp_f32_e32 v83, v82
	s_nop 0
	v_fma_f32 v84, -v82, v83, 1.0
	v_fmac_f32_e32 v83, v84, v83
	v_div_scale_f32 v84, vcc, 1.0, v81, 1.0
	v_mul_f32_e32 v85, v84, v83
	v_fma_f32 v86, -v82, v85, v84
	v_fmac_f32_e32 v85, v86, v83
	v_fma_f32 v82, -v82, v85, v84
	v_div_fmas_f32 v82, v82, v83, v85
	v_div_fixup_f32 v81, v82, v81, 1.0
	v_mul_f32_e32 v66, v66, v81
	v_mul_f32_e32 v68, v68, v81
	v_mul_f32_e32 v0, v0, v81
	v_mul_f32_e32 v67, v67, v81
	v_fma_f32 v65, v3, v68, v65
	v_fma_f32 v63, v5, v66, v63
	v_fma_f32 v64, v2, v67, v64
	v_fmac_f32_e32 v62, v4, v0
	v_mul_f32_e32 v0, v63, v63
	v_mul_f32_e32 v68, v65, v65
	v_fmac_f32_e32 v0, v62, v62
	v_fmac_f32_e32 v68, v64, v64
	v_add_f32_e32 v0, v0, v68
	v_mul_f32_e32 v68, v69, v81
	v_mul_f32_e32 v69, v70, v81
	v_mul_f32_e32 v70, v71, v81
	v_mul_f32_e32 v71, v72, v81
	v_fma_f32 v61, v15, v71, v61
	v_fma_f32 v59, v17, v69, v59
	v_fma_f32 v60, v14, v70, v60
	v_fmac_f32_e32 v58, v16, v68
	v_mul_f32_e32 v68, v59, v59
	v_mul_f32_e32 v69, v61, v61
	v_fmac_f32_e32 v68, v58, v58
	v_fmac_f32_e32 v69, v60, v60
	v_add_f32_e32 v68, v68, v69
	v_mul_f32_e32 v69, v74, v81
	v_mul_f32_e32 v71, v76, v81
	v_add_f32_e32 v0, v0, v68
	v_mul_f32_e32 v68, v73, v81
	v_mul_f32_e32 v70, v75, v81
	v_fma_f32 v57, v27, v71, v57
	v_fma_f32 v55, v29, v69, v55
	v_fma_f32 v56, v26, v70, v56
	v_fmac_f32_e32 v54, v28, v68
	v_mul_f32_e32 v68, v55, v55
	v_mul_f32_e32 v69, v57, v57
	v_fmac_f32_e32 v68, v54, v54
	v_fmac_f32_e32 v69, v56, v56
	v_add_f32_e32 v68, v68, v69
	v_add_f32_e32 v0, v68, v0
	v_mul_f32_e32 v68, v77, v81
	v_mul_f32_e32 v69, v78, v81
	v_mul_f32_e32 v70, v79, v81
	v_mul_f32_e32 v71, v80, v81
	v_lshl_add_u64 v[66:67], v[120:121], 0, v[126:127]
	v_fma_f32 v53, v39, v71, v53
	v_fma_f32 v52, v38, v70, v52
	v_fma_f32 v51, v41, v69, v51
	v_fmac_f32_e32 v50, v40, v68
	s_nop 1
	s_nop 1
	s_nop 1
	s_nop 1
	v_mul_f32_e32 v66, v51, v51
	v_mul_f32_e32 v67, v53, v53
	v_fmac_f32_e32 v66, v50, v50
	v_fmac_f32_e32 v67, v52, v52
	v_add_f32_e32 v66, v66, v67
	v_add_f32_e32 v0, v66, v0
	s_nop 1
	v_add_f32_dpp v0, v0, v0 quad_perm:[1,0,3,2] row_mask:0xf bank_mask:0xf bound_ctrl:1
	s_nop 1
	v_add_f32_dpp v0, v0, v0 quad_perm:[2,3,0,1] row_mask:0xf bank_mask:0xf bound_ctrl:1
	s_nop 1
	v_add_f32_dpp v0, v0, v0 row_half_mirror row_mask:0xf bank_mask:0xf bound_ctrl:1
	s_nop 1
	v_add_f32_dpp v0, v0, v0 row_mirror row_mask:0xf bank_mask:0xf bound_ctrl:1
	s_nop 0
	v_readlane_b32 s1, v0, 16
	v_readlane_b32 s6, v0, 48
	v_readlane_b32 s0, v0, 0
	v_readlane_b32 s2, v0, 32
	v_mov_b32_e32 v0, s1
	v_mov_b32_e32 v66, s6
	v_add_f32_e32 v0, s0, v0
	v_add_f32_e32 v66, s2, v66
	v_add_f32_e32 v0, v0, v66
	v_fmamk_f32 v0, v0, 0x3a800000, v188
	v_cmp_gt_f32_e32 vcc, s49, v0
	v_mul_f32_e32 v66, 0x4f800000, v0
	s_nop 0
	v_cndmask_b32_e32 v0, v0, v66, vcc
	v_sqrt_f32_e32 v66, v0
	s_nop 0
	v_add_u32_e32 v67, -1, v66
	v_fma_f32 v68, -v67, v66, v0
	v_cmp_ge_f32_e64 s[0:1], 0, v68
	v_add_u32_e32 v68, 1, v66
	s_nop 0
	v_cndmask_b32_e64 v67, v66, v67, s[0:1]
	v_fma_f32 v66, -v68, v66, v0
	v_cmp_lt_f32_e64 s[0:1], 0, v66
	s_nop 1
	v_cndmask_b32_e64 v66, v67, v68, s[0:1]
	v_mul_f32_e32 v67, 0x37800000, v66
	v_cndmask_b32_e32 v66, v66, v67, vcc
	v_cmp_class_f32_e32 vcc, v0, v189
	s_nop 1
	v_cndmask_b32_e32 v0, v66, v0, vcc
	v_div_scale_f32 v66, s[0:1], v0, v0, 1.0
	v_rcp_f32_e32 v67, v66
	s_nop 0
	v_fma_f32 v68, -v66, v67, 1.0
	v_fmac_f32_e32 v67, v68, v67
	v_div_scale_f32 v68, vcc, 1.0, v0, 1.0
	v_mul_f32_e32 v69, v68, v67
	v_fma_f32 v70, -v66, v69, v68
	v_fmac_f32_e32 v69, v70, v67
	v_fma_f32 v66, -v66, v69, v68
	v_div_fmas_f32 v66, v66, v67, v69
	v_div_fixup_f32 v0, v66, v0, 1.0
	v_mul_f32_e32 v63, v63, v0
	v_mul_f32_e32 v62, v62, v0
	v_mul_f32_e32 v59, v59, v0
	v_mul_f32_e32 v58, v58, v0
	v_mul_f32_e32 v55, v55, v0
	v_mul_f32_e32 v54, v54, v0
	v_mul_f32_e32 v51, v51, v0
	v_mul_f32_e32 v50, v50, v0
	v_cmp_lt_i32_e32 vcc, s61, v172
	v_lshl_add_u64 v[66:67], v[118:119], 0, v[124:125]
	v_mul_f32_e32 v65, v65, v0
	v_mul_f32_e32 v64, v64, v0
	v_fma_f32 v62, v8, v62, v10
	v_fma_f32 v63, v9, v63, v11
	v_mul_f32_e32 v61, v61, v0
	v_mul_f32_e32 v60, v60, v0
	v_fma_f32 v58, v20, v58, v22
	v_fma_f32 v59, v21, v59, v23
	v_mul_f32_e32 v57, v57, v0
	v_mul_f32_e32 v56, v56, v0
	v_fma_f32 v54, v32, v54, v34
	v_fma_f32 v55, v33, v55, v35
	v_mul_f32_e32 v53, v53, v0
	v_mul_f32_e32 v0, v52, v0
	v_fma_f32 v50, v44, v50, v46
	v_fma_f32 v51, v45, v51, v47
	s_or_b64 s[42:43], vcc, s[42:43]
	v_fma_f32 v64, v6, v64, v12
	v_fma_f32 v65, v7, v65, v13
	v_cvt_pk_bf16_f32 v62, v62, v63
	v_cvt_pk_bf16_f32 v63, v64, v65
	global_store_dwordx2 v[66:67], v[62:63], off
	v_fma_f32 v60, v18, v60, v24
	v_fma_f32 v61, v19, v61, v25
	v_cvt_pk_bf16_f32 v58, v58, v59
	v_cvt_pk_bf16_f32 v59, v60, v61
	global_store_dwordx2 v[66:67], v[58:59], off offset:512
	v_fma_f32 v56, v30, v56, v36
	v_fma_f32 v57, v31, v57, v37
	v_cvt_pk_bf16_f32 v54, v54, v55
	v_cvt_pk_bf16_f32 v55, v56, v57
	global_store_dwordx2 v[66:67], v[54:55], off offset:1024
	v_fma_f32 v0, v42, v0, v48
	v_fma_f32 v52, v43, v53, v49
	v_cvt_pk_bf16_f32 v50, v50, v51
	v_cvt_pk_bf16_f32 v51, v0, v52
	global_store_dwordx2 v[66:67], v[50:51], off offset:1536
	s_andn2_b64 exec, exec, s[42:43]
	s_cbranch_execnz .LBB0_33
